# ping-pong attention with the K/V staging moved into the MFMA segment (no group-dependent staging)
# speedup vs baseline: 1.0294x; 1.0294x over previous
.LBB0_1012:
	s_ashr_i32 s39, s0, 7
	s_lshl_b32 s4, s0, 9
	s_bfe_u32 s1, s0, 0x40003
	s_and_b32 s40, s4, 0xe00
	s_lshl_b32 s4, s39, 4
	s_or_b32 s4, s4, s1
	s_add_i32 s40, s40, s38
	s_ashr_i32 s5, s4, 31
	s_lshr_b32 s6, s0, 3
	s_lshl_b64 s[4:5], s[4:5], 12
	s_ashr_i32 s7, s40, 31
	s_add_u32 s4, s4, s40
	s_addc_u32 s5, s5, s7
	v_mov_b32_e32 v1, s5
	v_or_b32_e32 v0, s4, v202
	s_bfe_u32 s4, s6, 0x20002
	s_lshl_b32 s5, s39, 2
	s_or_b32 s4, s4, s5
	v_lshlrev_b64 v[0:1], 7, v[0:1]
	s_ashr_i32 s5, s4, 31
	v_lshl_add_u64 v[2:3], v[204:205], 0, v[0:1]
	v_or_b32_e32 v0, 0x1000, v0
	s_lshl_b64 s[4:5], s[4:5], 19
	v_lshl_add_u64 v[0:1], v[204:205], 0, v[0:1]
	v_lshl_add_u64 v[212:213], v[208:209], 0, s[4:5]
	global_load_dwordx4 v[130:133], v[2:3], off
	global_load_dwordx4 v[134:137], v[2:3], off offset:32
	global_load_dwordx4 v[138:141], v[2:3], off offset:64
	global_load_dwordx4 v[142:145], v[2:3], off offset:96
	global_load_dwordx4 v[146:149], v[0:1], off
	global_load_dwordx4 v[150:153], v[0:1], off offset:32
	global_load_dwordx4 v[154:157], v[0:1], off offset:64
	global_load_dwordx4 v[158:161], v[0:1], off offset:96
	v_lshl_add_u64 v[214:215], v[210:211], 0, s[4:5]
	global_load_dwordx4 v[0:3], v[212:213], off
	global_load_dwordx4 v[4:7], v[214:215], off
	s_mov_b64 s[6:7], 0x2000
	v_lshl_add_u64 v[182:183], v[212:213], 0, s[6:7]
	global_load_dwordx4 v[182:185], v[182:183], off
	global_load_dwordx4 v[178:181], v[214:215], off offset:128
	v_mov_b32_e32 v82, 0xf149f2ca
	s_mov_b32 s4, 0
	s_movk_i32 s42, 0x6c00
	s_movk_i32 s41, 0x4800
	s_mov_b32 s5, 0x9000
	v_mov_b32_e32 v162, 0
	v_mov_b32_e32 v163, 0
	v_mov_b32_e32 v164, 0
	v_mov_b32_e32 v165, 0
	v_mov_b32_e32 v174, 0
	v_mov_b32_e32 v175, 0
	v_mov_b32_e32 v176, 0
	v_mov_b32_e32 v177, 0
	v_mov_b32_e32 v166, 0
	v_mov_b32_e32 v167, 0
	v_mov_b32_e32 v168, 0
	v_mov_b32_e32 v169, 0
	v_mov_b32_e32 v170, 0
	v_mov_b32_e32 v171, 0
	v_mov_b32_e32 v172, 0
	v_mov_b32_e32 v173, 0
	v_mov_b32_e32 v83, v82
	v_mov_b32_e32 v84, v82
	v_mov_b32_e32 v85, v82
	v_mov_b32_e32 v86, v82
	v_mov_b32_e32 v87, v82
	v_mov_b32_e32 v88, v82
	v_mov_b32_e32 v89, v82
	v_mov_b32_e32 v90, v82
	v_mov_b32_e32 v91, v82
	v_mov_b32_e32 v92, v82
	v_mov_b32_e32 v93, v82
	v_mov_b32_e32 v94, v82
	v_mov_b32_e32 v95, v82
	v_mov_b32_e32 v96, v82
	v_mov_b32_e32 v97, v82
	v_mov_b32_e32 v66, v82
	v_mov_b32_e32 v67, v82
	v_mov_b32_e32 v68, v82
	v_mov_b32_e32 v69, v82
	v_mov_b32_e32 v70, v82
	v_mov_b32_e32 v71, v82
	v_mov_b32_e32 v72, v82
	v_mov_b32_e32 v73, v82
	v_mov_b32_e32 v74, v82
	v_mov_b32_e32 v75, v82
	v_mov_b32_e32 v76, v82
	v_mov_b32_e32 v77, v82
	v_mov_b32_e32 v78, v82
	v_mov_b32_e32 v79, v82
	v_mov_b32_e32 v80, v82
	v_mov_b32_e32 v81, v82
	s_waitcnt vmcnt(3)
	ds_write_b128 v203, v[0:3]
	s_waitcnt vmcnt(2)
	ds_write_b128 v203, v[4:7] offset:18432
	v_mov_b32_e32 v0, 0
	v_mov_b32_e32 v1, v0
	v_mov_b32_e32 v2, v0
	v_mov_b32_e32 v3, v0
	v_mov_b32_e32 v4, v0
	v_mov_b32_e32 v5, v0
	v_mov_b32_e32 v6, v0
	v_mov_b32_e32 v7, v0
	v_mov_b32_e32 v8, v0
	v_mov_b32_e32 v9, v0
	v_mov_b32_e32 v10, v0
	v_mov_b32_e32 v11, v0
	v_mov_b32_e32 v12, v0
	v_mov_b32_e32 v13, v0
	v_mov_b32_e32 v14, v0
	v_mov_b32_e32 v15, v0
	v_mov_b32_e32 v16, v0
	v_mov_b32_e32 v17, v0
	v_mov_b32_e32 v18, v0
	v_mov_b32_e32 v19, v0
	v_mov_b32_e32 v20, v0
	v_mov_b32_e32 v21, v0
	v_mov_b32_e32 v22, v0
	v_mov_b32_e32 v23, v0
	v_mov_b32_e32 v24, v0
	v_mov_b32_e32 v25, v0
	v_mov_b32_e32 v26, v0
	v_mov_b32_e32 v27, v0
	v_mov_b32_e32 v28, v0
	v_mov_b32_e32 v29, v0
	v_mov_b32_e32 v30, v0
	v_mov_b32_e32 v31, v0
	v_mov_b32_e32 v34, v0
	v_mov_b32_e32 v35, v0
	v_mov_b32_e32 v36, v0
	v_mov_b32_e32 v37, v0
	v_mov_b32_e32 v38, v0
	v_mov_b32_e32 v39, v0
	v_mov_b32_e32 v40, v0
	v_mov_b32_e32 v41, v0
	v_mov_b32_e32 v42, v0
	v_mov_b32_e32 v43, v0
	v_mov_b32_e32 v44, v0
	v_mov_b32_e32 v45, v0
	v_mov_b32_e32 v46, v0
	v_mov_b32_e32 v47, v0
	v_mov_b32_e32 v48, v0
	v_mov_b32_e32 v49, v0
	v_mov_b32_e32 v50, v0
	v_mov_b32_e32 v51, v0
	v_mov_b32_e32 v52, v0
	v_mov_b32_e32 v53, v0
	v_mov_b32_e32 v54, v0
	v_mov_b32_e32 v55, v0
	v_mov_b32_e32 v56, v0
	v_mov_b32_e32 v57, v0
	v_mov_b32_e32 v58, v0
	v_mov_b32_e32 v59, v0
	v_mov_b32_e32 v60, v0
	v_mov_b32_e32 v61, v0
	v_mov_b32_e32 v62, v0
	v_mov_b32_e32 v63, v0
	v_mov_b32_e32 v64, v0
	v_mov_b32_e32 v65, v0
	v_mov_b32_e32 v216, v0
	v_mov_b32_e32 v217, v0
	s_waitcnt lgkmcnt(0)
	s_barrier
	v_mov_b32_e32 v234, v245
	v_add_u32_e32 v235, s5, v32
	s_cmpk_lt_u32 s38, 0x100
	s_cselect_b32 s101, 0, 1
	v_mov_b32_e32 v186, 0
	v_mov_b32_e32 v187, 0
	v_mov_b32_e32 v188, 0
	v_mov_b32_e32 v189, 0
	v_mov_b32_e32 v190, 0
	v_mov_b32_e32 v191, 0
	v_mov_b32_e32 v192, 0
	v_mov_b32_e32 v193, 0
	v_mov_b32_e32 v218, 0
	v_mov_b32_e32 v219, 0
	v_mov_b32_e32 v220, 0
	v_mov_b32_e32 v221, 0
	v_mov_b32_e32 v222, 0
	v_mov_b32_e32 v223, 0
	v_mov_b32_e32 v224, 0
	v_mov_b32_e32 v225, 0
	ds_read_b128 v[226:229], v235
	ds_read_b128 v[230:233], v235 offset:4608
	s_cmp_eq_u32 s101, 0
	s_cbranch_scc1 .Lpp_enter
	s_barrier
.Lpp_enter:
.LBB0_1013:
	s_waitcnt lgkmcnt(1)
	v_mfma_f32_32x32x16_bf16 v[50:65], v[226:229], v[170:173], v[50:65]
	ds_read_b128 v[246:249], v235 offset:32
	v_mfma_f32_32x32x16_bf16 v[16:31], v[226:229], v[174:177], v[16:31]
	s_add_i32 s44, s4, 1
	s_and_b32 s43, s44, 1
	s_mul_i32 s43, s43, 0x2400
	s_waitcnt lgkmcnt(1)
	v_mfma_f32_32x32x16_bf16 v[34:49], v[230:233], v[170:173], v[34:49]
	ds_read_b128 v[226:229], v235 offset:4640
	v_add_u32_e32 v198, s43, v203
	v_add_u32_e32 v199, s42, v203
	v_mfma_f32_32x32x16_bf16 v[0:15], v[230:233], v[174:177], v[0:15]
	s_add_i32 s16, s4, 2
	s_min_u32 s16, s16, 63
	s_waitcnt vmcnt(0)
	s_waitcnt lgkmcnt(1)
	v_mfma_f32_32x32x16_bf16 v[50:65], v[246:249], v[166:169], v[50:65]
	ds_read_b128 v[230:233], v235 offset:64
	ds_write_b128 v199, v[178:181]
	v_mfma_f32_32x32x16_bf16 v[16:31], v[246:249], v[162:165], v[16:31]
	s_waitcnt lgkmcnt(2)
	v_mfma_f32_32x32x16_bf16 v[34:49], v[226:229], v[166:169], v[34:49]
	ds_read_b128 v[246:249], v235 offset:4672
	ds_write_b128 v198, v[182:185]
	v_mfma_f32_32x32x16_bf16 v[0:15], v[226:229], v[162:165], v[0:15]
	s_waitcnt lgkmcnt(3)
	v_mfma_f32_32x32x16_bf16 v[50:65], v[230:233], v[186:189], v[50:65]
	ds_read_b128 v[226:229], v235 offset:96
	s_lshl_b64 s[6:7], s[16:17], 13
	v_lshl_add_u64 v[182:183], v[212:213], 0, s[6:7]
	v_mfma_f32_32x32x16_bf16 v[16:31], v[230:233], v[218:221], v[16:31]
	global_load_dwordx4 v[182:185], v[182:183], off
	s_lshl_b64 s[6:7], s[16:17], 7
	s_waitcnt lgkmcnt(2)
	v_mfma_f32_32x32x16_bf16 v[34:49], v[246:249], v[186:189], v[34:49]
	ds_read_b128 v[230:233], v235 offset:4704
	v_lshl_add_u64 v[178:179], v[214:215], 0, s[6:7]
	v_mfma_f32_32x32x16_bf16 v[0:15], v[246:249], v[218:221], v[0:15]
	global_load_dwordx4 v[178:181], v[178:179], off
	s_waitcnt lgkmcnt(1)
	v_mfma_f32_32x32x16_bf16 v[50:65], v[226:229], v[190:193], v[50:65]
	ds_read_b128 v[246:249], v234
	v_mfma_f32_32x32x16_bf16 v[16:31], v[226:229], v[222:225], v[16:31]
	s_waitcnt lgkmcnt(1)
	v_mfma_f32_32x32x16_bf16 v[34:49], v[230:233], v[190:193], v[34:49]
	ds_read_b128 v[226:229], v234 offset:32
	v_mfma_f32_32x32x16_bf16 v[0:15], v[230:233], v[222:225], v[0:15]
	s_waitcnt lgkmcnt(1)
	v_mfma_f32_32x32x16_bf16 v[114:129], v[246:249], v[130:133], 0
	ds_read_b128 v[230:233], v234 offset:64
	v_mfma_f32_32x32x16_bf16 v[98:113], v[246:249], v[146:149], 0
	s_waitcnt lgkmcnt(1)
	v_mfma_f32_32x32x16_bf16 v[114:129], v[226:229], v[134:137], v[114:129]
	ds_read_b128 v[246:249], v234 offset:96
	v_mfma_f32_32x32x16_bf16 v[98:113], v[226:229], v[150:153], v[98:113]
	s_waitcnt lgkmcnt(1)
	v_mfma_f32_32x32x16_bf16 v[114:129], v[230:233], v[138:141], v[114:129]
	ds_read_b128 v[226:229], v234 offset:4608
	v_mfma_f32_32x32x16_bf16 v[98:113], v[230:233], v[154:157], v[98:113]
	s_waitcnt lgkmcnt(1)
	v_mfma_f32_32x32x16_bf16 v[114:129], v[246:249], v[142:145], v[114:129]
	ds_read_b128 v[230:233], v234 offset:4640
	v_mfma_f32_32x32x16_bf16 v[98:113], v[246:249], v[158:161], v[98:113]
	s_waitcnt lgkmcnt(1)
	v_mfma_f32_32x32x16_bf16 v[82:97], v[226:229], v[130:133], 0
	ds_read_b128 v[246:249], v234 offset:4672
	v_mfma_f32_32x32x16_bf16 v[66:81], v[226:229], v[146:149], 0
	s_waitcnt lgkmcnt(1)
	v_mfma_f32_32x32x16_bf16 v[82:97], v[230:233], v[134:137], v[82:97]
	ds_read_b128 v[226:229], v234 offset:4704
	v_mfma_f32_32x32x16_bf16 v[66:81], v[230:233], v[150:153], v[66:81]
	s_waitcnt lgkmcnt(1)
	v_mfma_f32_32x32x16_bf16 v[82:97], v[246:249], v[138:141], v[82:97]
	v_mfma_f32_32x32x16_bf16 v[66:81], v[246:249], v[154:157], v[66:81]
	s_waitcnt lgkmcnt(0)
	v_mfma_f32_32x32x16_bf16 v[82:97], v[226:229], v[142:145], v[82:97]
	v_mfma_f32_32x32x16_bf16 v[66:81], v[226:229], v[158:161], v[66:81]
	s_barrier
	v_exp_f32_e32 v114, v114
	v_exp_f32_e32 v115, v115
	v_exp_f32_e32 v116, v116
	v_exp_f32_e32 v117, v117
	v_exp_f32_e32 v118, v118
	v_exp_f32_e32 v119, v119
	v_exp_f32_e32 v120, v120
	v_exp_f32_e32 v121, v121
	v_cvt_pk_bf16_f32 v170, v114, v115
	v_add_f32_e32 v114, v114, v115
	v_exp_f32_e32 v122, v122
	v_exp_f32_e32 v123, v123
	v_cvt_pk_bf16_f32 v171, v116, v117
	v_add_f32_e32 v116, v116, v117
	v_add_f32_e32 v217, v217, v114
	v_exp_f32_e32 v124, v124
	v_exp_f32_e32 v125, v125
	v_cvt_pk_bf16_f32 v172, v118, v119
	v_add_f32_e32 v118, v118, v119
	v_add_f32_e32 v217, v217, v116
	v_exp_f32_e32 v126, v126
	v_exp_f32_e32 v127, v127
	v_cvt_pk_bf16_f32 v173, v120, v121
	v_add_f32_e32 v120, v120, v121
	v_add_f32_e32 v217, v217, v118
	v_exp_f32_e32 v128, v128
	v_exp_f32_e32 v129, v129
	v_cvt_pk_bf16_f32 v166, v122, v123
	v_add_f32_e32 v122, v122, v123
	v_add_f32_e32 v217, v217, v120
	v_exp_f32_e32 v98, v98
	v_exp_f32_e32 v99, v99
	v_cvt_pk_bf16_f32 v167, v124, v125
	v_add_f32_e32 v124, v124, v125
	v_add_f32_e32 v217, v217, v122
	v_exp_f32_e32 v100, v100
	v_exp_f32_e32 v101, v101
	v_cvt_pk_bf16_f32 v168, v126, v127
	v_add_f32_e32 v126, v126, v127
	v_add_f32_e32 v217, v217, v124
	v_exp_f32_e32 v102, v102
	v_exp_f32_e32 v103, v103
	v_cvt_pk_bf16_f32 v169, v128, v129
	v_add_f32_e32 v128, v128, v129
	v_add_f32_e32 v217, v217, v126
	v_exp_f32_e32 v104, v104
	v_exp_f32_e32 v105, v105
	v_cvt_pk_bf16_f32 v174, v98, v99
	v_add_f32_e32 v98, v98, v99
	v_add_f32_e32 v217, v217, v128
	v_exp_f32_e32 v106, v106
	v_exp_f32_e32 v107, v107
	v_cvt_pk_bf16_f32 v175, v100, v101
	v_add_f32_e32 v100, v100, v101
	v_add_f32_e32 v216, v216, v98
	v_exp_f32_e32 v108, v108
	v_exp_f32_e32 v109, v109
	v_cvt_pk_bf16_f32 v176, v102, v103
	v_add_f32_e32 v102, v102, v103
	v_add_f32_e32 v216, v216, v100
	v_exp_f32_e32 v110, v110
	v_exp_f32_e32 v111, v111
	v_cvt_pk_bf16_f32 v177, v104, v105
	v_add_f32_e32 v104, v104, v105
	v_add_f32_e32 v216, v216, v102
	v_exp_f32_e32 v112, v112
	v_exp_f32_e32 v113, v113
	v_cvt_pk_bf16_f32 v162, v106, v107
	v_add_f32_e32 v106, v106, v107
	v_add_f32_e32 v216, v216, v104
	v_cvt_pk_bf16_f32 v163, v108, v109
	v_add_f32_e32 v108, v108, v109
	v_add_f32_e32 v216, v216, v106
	v_cvt_pk_bf16_f32 v164, v110, v111
	v_add_f32_e32 v110, v110, v111
	v_add_f32_e32 v216, v216, v108
	v_cvt_pk_bf16_f32 v165, v112, v113
	v_add_f32_e32 v112, v112, v113
	v_add_f32_e32 v216, v216, v110
	v_add_f32_e32 v216, v216, v112
	v_exp_f32_e32 v82, v82
	v_exp_f32_e32 v83, v83
	v_exp_f32_e32 v84, v84
	v_exp_f32_e32 v85, v85
	v_exp_f32_e32 v86, v86
	v_exp_f32_e32 v87, v87
	v_exp_f32_e32 v88, v88
	v_exp_f32_e32 v89, v89
	v_cvt_pk_bf16_f32 v186, v82, v83
	v_add_f32_e32 v82, v82, v83
	v_exp_f32_e32 v90, v90
	v_exp_f32_e32 v91, v91
	v_cvt_pk_bf16_f32 v187, v84, v85
	v_add_f32_e32 v84, v84, v85
	v_add_f32_e32 v217, v217, v82
	v_exp_f32_e32 v92, v92
	v_exp_f32_e32 v93, v93
	v_cvt_pk_bf16_f32 v188, v86, v87
	v_add_f32_e32 v86, v86, v87
	v_add_f32_e32 v217, v217, v84
	v_exp_f32_e32 v94, v94
	v_exp_f32_e32 v95, v95
	v_cvt_pk_bf16_f32 v189, v88, v89
	v_add_f32_e32 v88, v88, v89
	v_add_f32_e32 v217, v217, v86
	v_exp_f32_e32 v96, v96
	v_exp_f32_e32 v97, v97
	v_cvt_pk_bf16_f32 v190, v90, v91
	v_add_f32_e32 v90, v90, v91
	v_add_f32_e32 v217, v217, v88
	v_exp_f32_e32 v66, v66
	v_exp_f32_e32 v67, v67
	v_cvt_pk_bf16_f32 v191, v92, v93
	v_add_f32_e32 v92, v92, v93
	v_add_f32_e32 v217, v217, v90
	v_exp_f32_e32 v68, v68
	v_exp_f32_e32 v69, v69
	v_cvt_pk_bf16_f32 v192, v94, v95
	v_add_f32_e32 v94, v94, v95
	v_add_f32_e32 v217, v217, v92
	v_exp_f32_e32 v70, v70
	v_exp_f32_e32 v71, v71
	v_cvt_pk_bf16_f32 v193, v96, v97
	v_add_f32_e32 v96, v96, v97
	v_add_f32_e32 v217, v217, v94
	v_exp_f32_e32 v72, v72
	v_exp_f32_e32 v73, v73
	v_cvt_pk_bf16_f32 v218, v66, v67
	v_add_f32_e32 v66, v66, v67
	v_add_f32_e32 v217, v217, v96
	v_exp_f32_e32 v74, v74
	v_exp_f32_e32 v75, v75
	v_cvt_pk_bf16_f32 v219, v68, v69
	v_add_f32_e32 v68, v68, v69
	v_add_f32_e32 v216, v216, v66
	v_exp_f32_e32 v76, v76
	v_exp_f32_e32 v77, v77
	v_cvt_pk_bf16_f32 v220, v70, v71
	v_add_f32_e32 v70, v70, v71
	v_add_f32_e32 v216, v216, v68
	v_exp_f32_e32 v78, v78
	v_exp_f32_e32 v79, v79
	v_cvt_pk_bf16_f32 v221, v72, v73
	v_add_f32_e32 v72, v72, v73
	v_add_f32_e32 v216, v216, v70
	v_exp_f32_e32 v80, v80
	v_exp_f32_e32 v81, v81
	v_cvt_pk_bf16_f32 v222, v74, v75
	v_add_f32_e32 v74, v74, v75
	v_add_f32_e32 v216, v216, v72
	v_cvt_pk_bf16_f32 v223, v76, v77
	v_add_f32_e32 v76, v76, v77
	v_add_f32_e32 v216, v216, v74
	v_cvt_pk_bf16_f32 v224, v78, v79
	v_add_f32_e32 v78, v78, v79
	v_add_f32_e32 v216, v216, v76
	v_cvt_pk_bf16_f32 v225, v80, v81
	v_add_f32_e32 v80, v80, v81
	v_add_f32_e32 v216, v216, v78
	v_add_f32_e32 v216, v216, v80
	v_add_u32_e32 v235, s41, v32
	v_add_u32_e32 v234, s43, v245
	ds_read_b128 v[226:229], v235
	ds_read_b128 v[230:233], v235 offset:4608
	s_waitcnt lgkmcnt(2)
	s_mov_b32 s6, s5
	s_mov_b32 s5, s41
	s_mov_b32 s41, s42
	s_mov_b32 s42, s6
	s_mov_b32 s4, s44
	s_cmp_eq_u32 s44, 63
	s_barrier
	s_cbranch_scc0 .LBB0_1013
	s_waitcnt lgkmcnt(1)
	v_mfma_f32_32x32x16_bf16 v[50:65], v[226:229], v[170:173], v[50:65]
	ds_read_b128 v[246:249], v235 offset:32
	v_mfma_f32_32x32x16_bf16 v[16:31], v[226:229], v[174:177], v[16:31]
	s_waitcnt lgkmcnt(1)
	v_mfma_f32_32x32x16_bf16 v[34:49], v[230:233], v[170:173], v[34:49]
	ds_read_b128 v[226:229], v235 offset:4640
	v_mfma_f32_32x32x16_bf16 v[0:15], v[230:233], v[174:177], v[0:15]
	s_waitcnt lgkmcnt(1)
	v_mfma_f32_32x32x16_bf16 v[50:65], v[246:249], v[166:169], v[50:65]
	ds_read_b128 v[230:233], v235 offset:64
	v_mfma_f32_32x32x16_bf16 v[16:31], v[246:249], v[162:165], v[16:31]
	s_waitcnt lgkmcnt(1)
	v_mfma_f32_32x32x16_bf16 v[34:49], v[226:229], v[166:169], v[34:49]
	ds_read_b128 v[246:249], v235 offset:4672
	v_mfma_f32_32x32x16_bf16 v[0:15], v[226:229], v[162:165], v[0:15]
	s_waitcnt lgkmcnt(1)
	v_mfma_f32_32x32x16_bf16 v[50:65], v[230:233], v[186:189], v[50:65]
	ds_read_b128 v[226:229], v235 offset:96
	v_mfma_f32_32x32x16_bf16 v[16:31], v[230:233], v[218:221], v[16:31]
	s_waitcnt lgkmcnt(1)
	v_mfma_f32_32x32x16_bf16 v[34:49], v[246:249], v[186:189], v[34:49]
	ds_read_b128 v[230:233], v235 offset:4704
	v_mfma_f32_32x32x16_bf16 v[0:15], v[246:249], v[218:221], v[0:15]
	s_waitcnt lgkmcnt(1)
	v_mfma_f32_32x32x16_bf16 v[50:65], v[226:229], v[190:193], v[50:65]
	ds_read_b128 v[246:249], v234
	v_mfma_f32_32x32x16_bf16 v[16:31], v[226:229], v[222:225], v[16:31]
	s_waitcnt lgkmcnt(1)
	v_mfma_f32_32x32x16_bf16 v[34:49], v[230:233], v[190:193], v[34:49]
	ds_read_b128 v[226:229], v234 offset:32
	v_mfma_f32_32x32x16_bf16 v[0:15], v[230:233], v[222:225], v[0:15]
	s_waitcnt lgkmcnt(1)
	v_mfma_f32_32x32x16_bf16 v[114:129], v[246:249], v[130:133], 0
	ds_read_b128 v[230:233], v234 offset:64
	v_mfma_f32_32x32x16_bf16 v[98:113], v[246:249], v[146:149], 0
	s_waitcnt lgkmcnt(1)
	v_mfma_f32_32x32x16_bf16 v[114:129], v[226:229], v[134:137], v[114:129]
	ds_read_b128 v[246:249], v234 offset:96
	v_mfma_f32_32x32x16_bf16 v[98:113], v[226:229], v[150:153], v[98:113]
	s_waitcnt lgkmcnt(1)
	v_mfma_f32_32x32x16_bf16 v[114:129], v[230:233], v[138:141], v[114:129]
	ds_read_b128 v[226:229], v234 offset:4608
	v_mfma_f32_32x32x16_bf16 v[98:113], v[230:233], v[154:157], v[98:113]
	s_waitcnt lgkmcnt(1)
	v_mfma_f32_32x32x16_bf16 v[114:129], v[246:249], v[142:145], v[114:129]
	ds_read_b128 v[230:233], v234 offset:4640
	v_mfma_f32_32x32x16_bf16 v[98:113], v[246:249], v[158:161], v[98:113]
	s_waitcnt lgkmcnt(1)
	v_mfma_f32_32x32x16_bf16 v[82:97], v[226:229], v[130:133], 0
	ds_read_b128 v[246:249], v234 offset:4672
	v_mfma_f32_32x32x16_bf16 v[66:81], v[226:229], v[146:149], 0
	s_waitcnt lgkmcnt(1)
	v_mfma_f32_32x32x16_bf16 v[82:97], v[230:233], v[134:137], v[82:97]
	ds_read_b128 v[226:229], v234 offset:4704
	v_mfma_f32_32x32x16_bf16 v[66:81], v[230:233], v[150:153], v[66:81]
	s_waitcnt lgkmcnt(1)
	v_mfma_f32_32x32x16_bf16 v[82:97], v[246:249], v[138:141], v[82:97]
	v_mfma_f32_32x32x16_bf16 v[66:81], v[246:249], v[154:157], v[66:81]
	s_waitcnt lgkmcnt(0)
	v_mfma_f32_32x32x16_bf16 v[82:97], v[226:229], v[142:145], v[82:97]
	v_mfma_f32_32x32x16_bf16 v[66:81], v[226:229], v[158:161], v[66:81]
	s_barrier
	v_exp_f32_e32 v114, v114
	v_exp_f32_e32 v115, v115
	v_exp_f32_e32 v116, v116
	v_exp_f32_e32 v117, v117
	v_exp_f32_e32 v118, v118
	v_exp_f32_e32 v119, v119
	v_exp_f32_e32 v120, v120
	v_exp_f32_e32 v121, v121
	v_cvt_pk_bf16_f32 v170, v114, v115
	v_add_f32_e32 v114, v114, v115
	v_exp_f32_e32 v122, v122
	v_exp_f32_e32 v123, v123
	v_cvt_pk_bf16_f32 v171, v116, v117
	v_add_f32_e32 v116, v116, v117
	v_add_f32_e32 v217, v217, v114
	v_exp_f32_e32 v124, v124
	v_exp_f32_e32 v125, v125
	v_cvt_pk_bf16_f32 v172, v118, v119
	v_add_f32_e32 v118, v118, v119
	v_add_f32_e32 v217, v217, v116
	v_exp_f32_e32 v126, v126
	v_exp_f32_e32 v127, v127
	v_cvt_pk_bf16_f32 v173, v120, v121
	v_add_f32_e32 v120, v120, v121
	v_add_f32_e32 v217, v217, v118
	v_exp_f32_e32 v128, v128
	v_exp_f32_e32 v129, v129
	v_cvt_pk_bf16_f32 v166, v122, v123
	v_add_f32_e32 v122, v122, v123
	v_add_f32_e32 v217, v217, v120
	v_exp_f32_e32 v98, v98
	v_exp_f32_e32 v99, v99
	v_cvt_pk_bf16_f32 v167, v124, v125
	v_add_f32_e32 v124, v124, v125
	v_add_f32_e32 v217, v217, v122
	v_exp_f32_e32 v100, v100
	v_exp_f32_e32 v101, v101
	v_cvt_pk_bf16_f32 v168, v126, v127
	v_add_f32_e32 v126, v126, v127
	v_add_f32_e32 v217, v217, v124
	v_exp_f32_e32 v102, v102
	v_exp_f32_e32 v103, v103
	v_cvt_pk_bf16_f32 v169, v128, v129
	v_add_f32_e32 v128, v128, v129
	v_add_f32_e32 v217, v217, v126
	v_exp_f32_e32 v104, v104
	v_exp_f32_e32 v105, v105
	v_cvt_pk_bf16_f32 v174, v98, v99
	v_add_f32_e32 v98, v98, v99
	v_add_f32_e32 v217, v217, v128
	v_exp_f32_e32 v106, v106
	v_exp_f32_e32 v107, v107
	v_cvt_pk_bf16_f32 v175, v100, v101
	v_add_f32_e32 v100, v100, v101
	v_add_f32_e32 v216, v216, v98
	v_exp_f32_e32 v108, v108
	v_exp_f32_e32 v109, v109
	v_cvt_pk_bf16_f32 v176, v102, v103
	v_add_f32_e32 v102, v102, v103
	v_add_f32_e32 v216, v216, v100
	v_exp_f32_e32 v110, v110
	v_exp_f32_e32 v111, v111
	v_cvt_pk_bf16_f32 v177, v104, v105
	v_add_f32_e32 v104, v104, v105
	v_add_f32_e32 v216, v216, v102
	v_exp_f32_e32 v112, v112
	v_exp_f32_e32 v113, v113
	v_cvt_pk_bf16_f32 v162, v106, v107
	v_add_f32_e32 v106, v106, v107
	v_add_f32_e32 v216, v216, v104
	v_cvt_pk_bf16_f32 v163, v108, v109
	v_add_f32_e32 v108, v108, v109
	v_add_f32_e32 v216, v216, v106
	v_cvt_pk_bf16_f32 v164, v110, v111
	v_add_f32_e32 v110, v110, v111
	v_add_f32_e32 v216, v216, v108
	v_cvt_pk_bf16_f32 v165, v112, v113
	v_add_f32_e32 v112, v112, v113
	v_add_f32_e32 v216, v216, v110
	v_add_f32_e32 v216, v216, v112
	s_waitcnt vmcnt(0)
	s_barrier
	s_cmp_eq_u32 s101, 0
	s_cbranch_scc0 .Lpp_exit
	s_barrier
